# grid barriers before the WOUT and MoE2 GEMM phases wait only for the workgroups of the same barrier group (their producer tiles), same write-back and invalidate
# baseline (speedup 1.0000x reference)
; __device__ __forceinline__ void grid_barrier(unsigned* ctl, unsigned k) {
;     asm volatile("s_waitcnt vmcnt(0)" ::: "memory");
;     __syncthreads();
;     if (threadIdx.x == 0) {
;         const unsigned g = blockIdx.x & 7u, G = gridDim.x, members = (G - g + 7u) >> 3, ngroups = G < 8u ? G : 8u;
;         __builtin_amdgcn_fence(__ATOMIC_RELEASE, "agent");
;         asm volatile("s_waitcnt vmcnt(0)" ::: "memory");
;         const unsigned old = __hip_atomic_fetch_add(ctl + 32 * g, 1u, __ATOMIC_RELAXED, __HIP_MEMORY_SCOPE_AGENT);
;         if (old == k * members - 1u) {
;             const unsigned old2 = __hip_atomic_fetch_add(ctl + 256, 1u, __ATOMIC_RELAXED, __HIP_MEMORY_SCOPE_AGENT);
;             if (old2 == k * ngroups - 1u) {
;                 for (unsigned q = 0; q < ngroups; ++q) __hip_atomic_store(ctl + 512 + 32 * q, k, __ATOMIC_RELAXED, __HIP_MEMORY_SCOPE_AGENT);
.LBB0_9:
	s_or_b64 exec, exec, s[8:9]
	s_sub_i32 s12, s16, s56
	s_waitcnt vmcnt(0)
	v_readfirstlane_b32 s6, v1
	s_nop 1
	v_add_u32_e32 v0, s6, v0
	s_mul_i32 s6, s12, s61
	s_add_i32 s6, s6, -1
	v_cmp_eq_u32_e32 vcc, s6, v0
	s_mov_b64 s[10:11], -1
	s_cmp_eq_u32 s16, 6
	s_cselect_b64 s[10:11], 0, s[10:11]
	s_cmp_eq_u32 s16, 10
	s_cselect_b64 s[10:11], 0, s[10:11]
	s_cmp_eq_u32 s16, 17
	s_cselect_b64 s[10:11], 0, s[10:11]
	s_cmp_eq_u32 s16, 21
	s_cselect_b64 s[10:11], 0, s[10:11]
	s_nop 1
	s_and_b64 vcc, vcc, s[10:11]
	s_and_saveexec_b64 s[6:7], vcc
	s_cbranch_execz .LBB0_15
	s_mov_b64 s[10:11], exec
	v_mbcnt_lo_u32_b32 v0, s10, 0
	v_mbcnt_hi_u32_b32 v0, s11, v0
	v_cmp_eq_u32_e32 vcc, 0, v0
	s_and_saveexec_b64 s[8:9], vcc
	s_cbranch_execz .LBB0_12
	s_bcnt1_i32_b64 s10, s[10:11]
	v_mov_b32_e32 v1, s10
	global_atomic_add v1, v189, v1, s[86:87] offset:1024 sc0
.LBB0_12:
	s_or_b64 exec, exec, s[8:9]
	s_waitcnt vmcnt(0)
	v_readfirstlane_b32 s8, v1
	s_nop 1
	v_add_u32_e32 v0, s8, v0
	v_readlane_b32 s8, v252, 4
	s_cmp_gt_u32 s16, 6
	s_addc_u32 s9, 0, 0
	s_cmp_gt_u32 s16, 10
	s_addc_u32 s9, s9, 0
	s_cmp_gt_u32 s16, 17
	s_addc_u32 s9, s9, 0
	s_cmp_gt_u32 s16, 21
	s_addc_u32 s9, s9, 0
	s_sub_i32 s9, s12, s9
	s_mul_i32 s8, s9, s8
	s_add_i32 s8, s8, -1
	v_cmp_eq_u32_e32 vcc, s8, v0
	v_readlane_b32 s8, v254, 15
	v_readlane_b32 s9, v254, 16
	s_and_b64 s[8:9], vcc, s[8:9]
	s_and_b64 exec, exec, s[8:9]
	s_cbranch_execz .LBB0_15
	v_readlane_b32 s8, v254, 29
	v_mov_b32_e32 v0, s12
	v_readlane_b32 s9, v254, 30
	v_readlane_b32 s10, v252, 4

; __device__ __forceinline__ void grid_barrier(unsigned* ctl, unsigned k) {
;     ...
;         const unsigned old = __hip_atomic_fetch_add(ctl + 32 * g, 1u, __ATOMIC_RELAXED, __HIP_MEMORY_SCOPE_AGENT);
;         if (old == k * members - 1u) {
;             const unsigned old2 = __hip_atomic_fetch_add(ctl + 256, 1u, __ATOMIC_RELAXED, __HIP_MEMORY_SCOPE_AGENT);
;             if (old2 == k * ngroups - 1u) {
;                 for (unsigned q = 0; q < ngroups; ++q) __hip_atomic_store(ctl + 512 + 32 * q, k, __ATOMIC_RELAXED, __HIP_MEMORY_SCOPE_AGENT);
;             }
;         }
;         while (__hip_atomic_load(ctl + 512 + 32 * g, __ATOMIC_RELAXED, __HIP_MEMORY_SCOPE_AGENT) < k) __builtin_amdgcn_s_sleep(1);
.LBB0_15:
	s_or_b64 exec, exec, s[6:7]
	s_mul_i32 s9, s12, s61
	s_mov_b32 s10, 0
	s_cmp_eq_u32 s16, 6
	s_cselect_b32 s10, 1, s10
	s_cmp_eq_u32 s16, 10
	s_cselect_b32 s10, 1, s10
	s_cmp_eq_u32 s16, 17
	s_cselect_b32 s10, 1, s10
	s_cmp_eq_u32 s16, 21
	s_cselect_b32 s10, 1, s10
	s_cmp_lg_u32 s10, 0
	s_cselect_b32 s9, s9, s12
	s_cselect_b32 s8, 0, 0x800
	v_mov_b32_e32 v1, s8
	global_load_dword v0, v1, s[72:73] sc1
	s_waitcnt vmcnt(0)
	v_cmp_le_u32_e32 vcc, s9, v0
	s_cbranch_vccnz .LBB0_17
.LBB0_16:
	s_sleep 1
	global_load_dword v0, v1, s[72:73] sc1
	s_waitcnt vmcnt(0)
	v_cmp_gt_u32_e32 vcc, s9, v0
	s_cbranch_vccnz .LBB0_16
